# SSD pass-B z read-modify-write: 16 serialized global round trips per chunk hoisted into one batch of loads after the staging barrier
# speedup vs baseline: 1.1601x; 1.0246x over previous
.Lcb_31495_3:
	s_or_b64 exec, exec, s[54:55]
	s_waitcnt vmcnt(0)
	ds_write_b128 v120, v[66:69]
	ds_write_b128 v120, v[62:65] offset:62464
	ds_write_b128 v122, v[36:39]
	ds_write_b128 v122, v[40:43] offset:62464
	ds_write_b128 v124, v[44:47]
	ds_write_b128 v124, v[48:51] offset:62464
	ds_write_b128 v126, v[52:55]
	ds_write_b128 v126, v[56:59] offset:62464
	s_add_i32 s82, s82, 1
	s_cmp_ge_u32 s82, s68
	s_waitcnt lgkmcnt(0)
	s_barrier
	v_add_u32_e32 v202, s77, v163
	v_ashrrev_i32_e32 v203, 31, v202
	v_lshlrev_b64 v[202:203], 12, v[202:203]
	v_lshl_add_u64 v[202:203], v[152:153], 0, v[202:203]
	v_add_u32_e32 v204, s77, v170
	v_ashrrev_i32_e32 v205, 31, v204
	v_lshlrev_b64 v[204:205], 12, v[204:205]
	v_lshl_add_u64 v[204:205], v[152:153], 0, v[204:205]
	v_add_u32_e32 v206, s77, v172
	v_ashrrev_i32_e32 v207, 31, v206
	v_lshlrev_b64 v[206:207], 12, v[206:207]
	v_lshl_add_u64 v[206:207], v[152:153], 0, v[206:207]
	v_add_u32_e32 v208, s77, v174
	v_ashrrev_i32_e32 v209, 31, v208
	v_lshlrev_b64 v[208:209], 12, v[208:209]
	v_lshl_add_u64 v[208:209], v[152:153], 0, v[208:209]
	global_load_ushort v210, v[202:203], off
	global_load_ushort v211, v[204:205], off
	global_load_ushort v240, v[206:207], off
	global_load_ushort v241, v[208:209], off offset:96
	global_load_ushort v242, v[208:209], off
	global_load_ushort v243, v[202:203], off offset:32
	global_load_ushort v244, v[204:205], off offset:32
	global_load_ushort v245, v[206:207], off offset:32
	global_load_ushort v246, v[208:209], off offset:32
	global_load_ushort v247, v[202:203], off offset:64
	global_load_ushort v248, v[204:205], off offset:64
	global_load_ushort v249, v[206:207], off offset:64
	global_load_ushort v250, v[208:209], off offset:64
	global_load_ushort v251, v[202:203], off offset:96
	global_load_ushort v252, v[204:205], off offset:96
	global_load_ushort v253, v[206:207], off offset:96
	s_cbranch_scc1 .LBB0_1708
	s_add_i32 s2, s74, 1
	s_cmpk_lt_i32 s74, 0xff
	s_cselect_b64 s[54:55], -1, 0
	s_and_b64 s[56:57], s[54:55], exec
	s_mul_i32 s90, s2, 0xc00
	v_mov_b32_e32 v40, v0
	v_mov_b32_e32 v41, v0
	s_cselect_b32 s74, 64, 16
	s_mul_hi_i32 s75, s2, 0xc00
	s_add_u32 s56, s90, s1
	v_mov_b32_e32 v42, v0
	v_mov_b32_e32 v43, v0
	v_mov_b64_e32 v[36:37], v[40:41]
	v_cmp_gt_u32_e32 vcc, s74, v107
	s_addc_u32 s57, s75, 0
	v_mov_b64_e32 v[38:39], v[42:43]
	s_and_saveexec_b64 s[58:59], vcc
	s_cbranch_execz .LBB0_1695
	v_lshl_add_u64 v[2:3], s[56:57], 0, v[112:113]
	v_lshlrev_b64 v[2:3], 7, v[2:3]
	v_lshl_add_u64 v[2:3], v[100:101], 0, v[2:3]
	global_load_dwordx4 v[36:39], v[2:3], off

.LBB0_1740:
	s_or_b64 exec, exec, s[54:55]
	ds_read_b128 v[60:63], v196
	ds_read_b128 v[64:67], v199
	v_bfe_u32 v3, v2, 16, 1
	v_add3_u32 v2, v2, v3, s85
	ds_write_b16_d16_hi v195, v2
	s_waitcnt lgkmcnt(2)
	v_sub_f32_e32 v2, v139, v60
	v_sub_f32_e32 v60, v139, v63
	v_mul_f32_e32 v60, 0x3fb8aa3b, v60
	v_exp_f32_e32 v69, v60
	s_waitcnt lgkmcnt(1)
	v_sub_f32_e32 v60, v139, v64
	v_mul_f32_e32 v60, 0x3fb8aa3b, v60
	v_exp_f32_e32 v70, v60
	v_sub_f32_e32 v60, v139, v65
	v_mul_f32_e32 v60, 0x3fb8aa3b, v60
	v_sub_f32_e32 v3, v139, v61
	v_exp_f32_e32 v72, v60
	v_sub_f32_e32 v60, v139, v66
	v_mul_f32_e32 v3, 0x3fb8aa3b, v3
	v_mul_f32_e32 v60, 0x3fb8aa3b, v60
	v_sub_f32_e32 v64, v139, v67
	v_exp_f32_e32 v68, v3
	v_sub_f32_e32 v3, v139, v62
	v_exp_f32_e32 v71, v60
	ds_read_b128 v[60:63], v198
	v_mul_f32_e32 v64, 0x3fb8aa3b, v64
	v_mul_f32_e32 v2, 0x3fb8aa3b, v2
	v_mul_f32_e32 v3, 0x3fb8aa3b, v3
	v_exp_f32_e32 v73, v64
	ds_read_b128 v[64:67], v197 offset:35840
	v_exp_f32_e32 v2, v2
	v_exp_f32_e32 v3, v3
	s_waitcnt lgkmcnt(1)
	v_mov_b32_e32 v74, v60
	v_mov_b32_e32 v75, v62
	v_mov_b32_e32 v62, v61
	v_pk_mul_f32 v[2:3], v[74:75], v[2:3]
	v_pk_mul_f32 v[60:61], v[62:63], v[68:69]
	s_waitcnt lgkmcnt(0)
	v_lshlrev_b32_e32 v63, 16, v65
	v_lshlrev_b32_e32 v62, 16, v64
	v_pk_mul_f32 v[2:3], v[2:3], v[62:63]
	v_and_b32_e32 v63, 0xffff0000, v65
	v_and_b32_e32 v62, 0xffff0000, v64
	v_pk_mul_f32 v[60:61], v[60:61], v[62:63]
	v_and_b32_sdwa v62, v3, v224 dst_sel:DWORD dst_unused:UNUSED_PAD src0_sel:WORD_1 src1_sel:DWORD
	v_and_b32_sdwa v63, v2, v224 dst_sel:DWORD dst_unused:UNUSED_PAD src0_sel:WORD_1 src1_sel:DWORD
	v_add3_u32 v2, v2, v63, s85
	v_add3_u32 v3, v3, v62, s85
	v_and_b32_sdwa v62, v61, v224 dst_sel:DWORD dst_unused:UNUSED_PAD src0_sel:WORD_1 src1_sel:DWORD
	v_and_b32_sdwa v63, v60, v224 dst_sel:DWORD dst_unused:UNUSED_PAD src0_sel:WORD_1 src1_sel:DWORD
	v_add3_u32 v64, v61, v62, s85
	v_add3_u32 v65, v60, v63, s85
	ds_read_b128 v[60:63], v200
	v_and_b32_e32 v64, 0xffff0000, v64
	v_and_b32_e32 v68, 0xffff0000, v65
	v_or_b32_sdwa v65, v64, v3 dst_sel:DWORD dst_unused:UNUSED_PAD src0_sel:DWORD src1_sel:WORD_1
	v_or_b32_sdwa v64, v68, v2 dst_sel:DWORD dst_unused:UNUSED_PAD src0_sel:DWORD src1_sel:WORD_1
	s_waitcnt lgkmcnt(0)
	v_mov_b32_e32 v2, v60
	v_mov_b32_e32 v3, v62
	v_mov_b32_e32 v62, v61
	v_pk_mul_f32 v[2:3], v[2:3], v[70:71]
	v_pk_mul_f32 v[60:61], v[62:63], v[72:73]
	v_lshlrev_b32_e32 v63, 16, v67
	v_lshlrev_b32_e32 v62, 16, v66
	v_pk_mul_f32 v[2:3], v[2:3], v[62:63]
	v_and_b32_e32 v63, 0xffff0000, v67
	v_and_b32_e32 v62, 0xffff0000, v66
	v_pk_mul_f32 v[60:61], v[60:61], v[62:63]
	v_cvt_pk_bf16_f32 v67, v3, v61
	v_cvt_pk_bf16_f32 v66, v2, v60
	ds_write_b128 v197, v[64:67] offset:62464
	ds_read_b128 v[60:63], v196
	ds_read_b128 v[64:67], v199
	v_cmp_gt_i32_e32 vcc, s76, v163
	s_waitcnt lgkmcnt(1)
	v_sub_f32_e32 v2, v139, v60
	v_mul_f32_e32 v2, 0x3fb8aa3b, v2
	v_exp_f32_e32 v68, v2
	v_sub_f32_e32 v2, v139, v61
	v_mul_f32_e32 v2, 0x3fb8aa3b, v2
	v_exp_f32_e32 v70, v2
	v_sub_f32_e32 v2, v139, v62
	v_mul_f32_e32 v2, 0x3fb8aa3b, v2
	v_exp_f32_e32 v69, v2
	v_sub_f32_e32 v2, v139, v63
	v_mul_f32_e32 v2, 0x3fb8aa3b, v2
	v_exp_f32_e32 v71, v2
	s_waitcnt lgkmcnt(0)
	v_sub_f32_e32 v2, v139, v64
	v_sub_f32_e32 v3, v139, v66
	v_mul_f32_e32 v2, 0x3fb8aa3b, v2
	v_mul_f32_e32 v3, 0x3fb8aa3b, v3
	ds_read_b128 v[60:63], v198
	v_exp_f32_e32 v72, v2
	v_sub_f32_e32 v2, v139, v65
	v_exp_f32_e32 v73, v3
	v_sub_f32_e32 v3, v139, v67
	ds_read_b128 v[64:67], v201 offset:35840
	s_waitcnt lgkmcnt(1)
	v_mov_b32_e32 v74, v60
	v_mov_b32_e32 v75, v62
	v_mov_b32_e32 v62, v61
	v_pk_mul_f32 v[68:69], v[74:75], v[68:69]
	v_pk_mul_f32 v[60:61], v[62:63], v[70:71]
	s_waitcnt lgkmcnt(0)
	v_lshlrev_b32_e32 v63, 16, v65
	v_lshlrev_b32_e32 v62, 16, v64
	v_pk_mul_f32 v[62:63], v[68:69], v[62:63]
	v_and_b32_e32 v65, 0xffff0000, v65
	v_and_b32_e32 v64, 0xffff0000, v64
	v_pk_mul_f32 v[60:61], v[60:61], v[64:65]
	v_and_b32_sdwa v64, v63, v224 dst_sel:DWORD dst_unused:UNUSED_PAD src0_sel:WORD_1 src1_sel:DWORD
	v_and_b32_sdwa v65, v62, v224 dst_sel:DWORD dst_unused:UNUSED_PAD src0_sel:WORD_1 src1_sel:DWORD
	v_add3_u32 v68, v62, v65, s85
	v_add3_u32 v64, v63, v64, s85
	v_and_b32_sdwa v62, v61, v224 dst_sel:DWORD dst_unused:UNUSED_PAD src0_sel:WORD_1 src1_sel:DWORD
	v_and_b32_sdwa v63, v60, v224 dst_sel:DWORD dst_unused:UNUSED_PAD src0_sel:WORD_1 src1_sel:DWORD
	v_add3_u32 v65, v61, v62, s85
	v_add3_u32 v69, v60, v63, s85
	ds_read_b128 v[60:63], v200
	v_mul_f32_e32 v2, 0x3fb8aa3b, v2
	v_mul_f32_e32 v3, 0x3fb8aa3b, v3
	v_exp_f32_e32 v2, v2
	v_exp_f32_e32 v3, v3
	v_and_b32_e32 v65, 0xffff0000, v65
	v_and_b32_e32 v69, 0xffff0000, v69
	v_or_b32_sdwa v65, v65, v64 dst_sel:DWORD dst_unused:UNUSED_PAD src0_sel:DWORD src1_sel:WORD_1
	v_or_b32_sdwa v64, v69, v68 dst_sel:DWORD dst_unused:UNUSED_PAD src0_sel:DWORD src1_sel:WORD_1
	s_waitcnt lgkmcnt(0)
	v_mov_b32_e32 v68, v60
	v_mov_b32_e32 v69, v62
	v_pk_mul_f32 v[68:69], v[68:69], v[72:73]
	v_mov_b32_e32 v62, v61
	v_lshlrev_b32_e32 v61, 16, v67
	v_lshlrev_b32_e32 v60, 16, v66
	v_pk_mul_f32 v[2:3], v[62:63], v[2:3]
	v_pk_mul_f32 v[60:61], v[68:69], v[60:61]
	v_and_b32_e32 v63, 0xffff0000, v67
	v_and_b32_e32 v62, 0xffff0000, v66
	v_pk_mul_f32 v[2:3], v[2:3], v[62:63]
	v_cvt_pk_bf16_f32 v67, v61, v3
	v_cvt_pk_bf16_f32 v66, v60, v2
	ds_write_b128 v201, v[64:67] offset:62464
	s_waitcnt lgkmcnt(0)
	s_barrier
	ds_read_b128 v[60:63], v164
	ds_read_b128 v[64:67], v102 offset:35840
	ds_read_b128 v[68:71], v102 offset:38144
	ds_read_b128 v[72:75], v102 offset:40448
	ds_read_b128 v[76:79], v102 offset:42752
	ds_read_b128 v[88:91], v164 offset:64
	s_waitcnt lgkmcnt(2)
	v_mfma_f32_16x16x32_bf16 v[84:87], v[60:63], v[72:75], 0
	ds_read_b128 v[72:75], v102 offset:35904
	v_mfma_f32_16x16x32_bf16 v[64:67], v[60:63], v[64:67], 0
	s_waitcnt lgkmcnt(0)
	v_mfma_f32_16x16x32_bf16 v[80:83], v[88:91], v[72:75], v[64:67]
	v_mfma_f32_16x16x32_bf16 v[68:71], v[60:63], v[68:71], 0
	s_nop 4
	ds_read_b128 v[64:67], v102 offset:38208
	v_mfma_f32_16x16x32_bf16 v[60:63], v[60:63], v[76:79], 0
	s_waitcnt lgkmcnt(0)
	v_mfma_f32_16x16x32_bf16 v[72:75], v[88:91], v[64:67], v[68:71]
	ds_read_b128 v[64:67], v102 offset:40512
	ds_read_b128 v[76:79], v102 offset:42816
	s_waitcnt lgkmcnt(1)
	v_mfma_f32_16x16x32_bf16 v[68:71], v[88:91], v[64:67], v[84:87]
	ds_read_b128 v[64:67], v157
	s_nop 1
	ds_read_b128 v[84:87], v158 offset:49408
	s_waitcnt lgkmcnt(2)
	v_mfma_f32_16x16x32_bf16 v[60:63], v[88:91], v[76:79], v[60:63]
	ds_read_b128 v[76:79], v158 offset:45056
	ds_read_b128 v[88:91], v158 offset:53760
	ds_read_b128 v[92:95], v158 offset:58112
	ds_read_b128 v[228:231], v157 offset:64
	s_waitcnt lgkmcnt(3)
	v_mfma_f32_16x16x32_bf16 v[76:79], v[64:67], v[76:79], 0
	v_mfma_f32_16x16x32_bf16 v[84:87], v[64:67], v[84:87], 0
	s_waitcnt lgkmcnt(2)
	v_mfma_f32_16x16x32_bf16 v[88:91], v[64:67], v[88:91], 0
	s_waitcnt lgkmcnt(1)
	v_mfma_f32_16x16x32_bf16 v[64:67], v[64:67], v[92:95], 0
	ds_read_b128 v[92:95], v158 offset:45120
	s_waitcnt lgkmcnt(0)
	v_mfma_f32_16x16x32_bf16 v[76:79], v[228:231], v[92:95], v[76:79]
	ds_read_b128 v[92:95], v158 offset:49472
	s_waitcnt lgkmcnt(0)
	v_mfma_f32_16x16x32_bf16 v[84:87], v[228:231], v[92:95], v[84:87]
	ds_read_b128 v[92:95], v158 offset:53824
	ds_read_b128 v[232:235], v158 offset:58176
	s_waitcnt lgkmcnt(1)
	v_mfma_f32_16x16x32_bf16 v[88:91], v[228:231], v[92:95], v[88:91]
	ds_read_b128 v[92:95], v157 offset:128
	s_waitcnt lgkmcnt(1)
	v_mfma_f32_16x16x32_bf16 v[64:67], v[228:231], v[232:235], v[64:67]
	ds_read_b128 v[228:231], v158 offset:45184
	s_waitcnt lgkmcnt(0)
	v_mfma_f32_16x16x32_bf16 v[76:79], v[92:95], v[228:231], v[76:79]
	ds_read_b128 v[228:231], v158 offset:49536
	s_waitcnt lgkmcnt(0)
	v_mfma_f32_16x16x32_bf16 v[84:87], v[92:95], v[228:231], v[84:87]
	ds_read_b128 v[228:231], v158 offset:53888
	ds_read_b128 v[232:235], v158 offset:58240
	ds_read_b128 v[236:239], v157 offset:192
	s_waitcnt lgkmcnt(2)
	v_mfma_f32_16x16x32_bf16 v[228:231], v[92:95], v[228:231], v[88:91]
	s_nop 2
	ds_read_b128 v[88:91], v158 offset:45248
	s_waitcnt lgkmcnt(0)
	v_mfma_f32_16x16x32_bf16 v[88:91], v[236:239], v[88:91], v[76:79]
	s_nop 2
	ds_read_b128 v[76:79], v158 offset:49600
	v_mfma_f32_16x16x32_bf16 v[64:67], v[92:95], v[232:235], v[64:67]
	s_waitcnt lgkmcnt(0)
	v_mfma_f32_16x16x32_bf16 v[84:87], v[236:239], v[76:79], v[84:87]
	ds_read_b128 v[76:79], v158 offset:53952
	ds_read_b128 v[232:235], v158 offset:58304
	ds_read_b128 v[92:95], v220
	ds_read_b64 v[154:155], v225 offset:35840
	s_waitcnt lgkmcnt(3)
	v_mfma_f32_16x16x32_bf16 v[76:79], v[236:239], v[76:79], v[228:231]
	s_waitcnt lgkmcnt(1)
	v_mul_f32_e32 v2, 0x3fb8aa3b, v92
	s_nop 0
	v_exp_f32_e32 v231, v2
	v_mfma_f32_16x16x32_bf16 v[64:67], v[236:239], v[232:235], v[64:67]
	v_add_u32_e32 v2, s77, v163
	v_mov_b32_e32 v228, 0
	v_ashrrev_i32_e32 v3, 31, v2
	v_mov_b32_e32 v229, 0
	s_waitcnt vmcnt(0)
	s_and_saveexec_b64 s[54:55], vcc
	s_cbranch_execz .LBB0_1742
	v_lshlrev_b64 v[232:233], 12, v[2:3]
	v_lshl_add_u64 v[232:233], v[152:153], 0, v[232:233]
	s_waitcnt lgkmcnt(0)
	v_lshlrev_b32_e32 v234, 16, v154
	v_fma_f32 v80, v88, v231, v80
	v_lshlrev_b32_e32 v235, 16, v210
	v_mul_f32_e32 v92, 0xbfb8aa3b, v235
	v_exp_f32_e32 v92, v92
	s_nop 0
	v_add_f32_e32 v92, 1.0, v92
	v_rcp_f32_e32 v149, v92
	s_nop 0
	v_pk_mul_f32 v[234:235], v[148:149], v[234:235]
	s_nop 0
	v_add_f32_e32 v80, v80, v234
	v_mul_f32_e32 v80, v80, v235
	v_bfe_u32 v88, v80, 16, 1
	v_add3_u32 v88, v80, v88, s85
	v_mul_f32_e32 v229, v80, v80
	global_store_short_d16_hi v[232:233], v88, off
.LBB0_1742:
	s_or_b64 exec, exec, s[54:55]
	v_mul_f32_e32 v80, 0x3fb8aa3b, v93
	v_exp_f32_e32 v232, v80
	v_add_u32_e32 v92, s77, v170
	v_cmp_gt_i32_e64 s[54:55], s76, v170
	v_ashrrev_i32_e32 v93, 31, v92
	v_mov_b32_e32 v230, 0
	s_and_saveexec_b64 s[56:57], s[54:55]
	s_cbranch_execz .LBB0_1744
	v_lshlrev_b64 v[234:235], 12, v[92:93]
	v_lshl_add_u64 v[234:235], v[152:153], 0, v[234:235]
	s_waitcnt lgkmcnt(0)
	v_and_b32_e32 v236, 0xffff0000, v154
	v_fma_f32 v88, v89, v232, v81
	v_lshlrev_b32_e32 v237, 16, v211
	v_mul_f32_e32 v80, 0xbfb8aa3b, v237
	v_exp_f32_e32 v80, v80
	s_nop 0
	v_add_f32_e32 v80, 1.0, v80
	v_rcp_f32_e32 v149, v80
	s_nop 0
	v_pk_mul_f32 v[80:81], v[148:149], v[236:237]
	s_nop 0
	v_add_f32_e32 v80, v88, v80
	v_mul_f32_e32 v80, v80, v81
	v_bfe_u32 v81, v80, 16, 1
	v_add3_u32 v81, v80, v81, s85
	v_mul_f32_e32 v230, v80, v80
	global_store_short_d16_hi v[234:235], v81, off
.LBB0_1744:
	s_or_b64 exec, exec, s[56:57]
	v_mul_f32_e32 v80, 0x3fb8aa3b, v94
	s_waitcnt lgkmcnt(0)
	v_exp_f32_e32 v154, v80
	v_add_u32_e32 v80, s77, v172
	v_cmp_gt_i32_e64 s[56:57], s76, v172
	v_ashrrev_i32_e32 v81, 31, v80
	s_and_saveexec_b64 s[58:59], s[56:57]
	s_cbranch_execz .LBB0_1746
	v_lshlrev_b64 v[88:89], 12, v[80:81]
	v_lshl_add_u64 v[88:89], v[152:153], 0, v[88:89]
	v_lshlrev_b32_e32 v234, 16, v155
	v_fma_f32 v82, v90, v154, v82
	v_lshlrev_b32_e32 v235, 16, v240
	v_mul_f32_e32 v94, 0xbfb8aa3b, v235
	v_exp_f32_e32 v94, v94
	s_nop 0
	v_add_f32_e32 v94, 1.0, v94
	v_rcp_f32_e32 v149, v94
	s_nop 0
	v_pk_mul_f32 v[234:235], v[148:149], v[234:235]
	s_nop 0
	v_add_f32_e32 v82, v82, v234
	v_mul_f32_e32 v82, v82, v235
	v_bfe_u32 v90, v82, 16, 1
	v_add3_u32 v90, v82, v90, s85
	v_mul_f32_e32 v228, v82, v82
	global_store_short_d16_hi v[88:89], v90, off

.LBB0_1759:
	v_lshlrev_b64 v[64:65], 12, v[88:89]
	v_lshl_add_u64 v[64:65], v[152:153], 0, v[64:65]
	s_waitcnt lgkmcnt(0)
	v_and_b32_e32 v60, 0xffff0000, v69
	v_fmac_f32_e32 v63, v67, v94
	v_lshlrev_b32_e32 v61, 16, v241
	v_mul_f32_e32 v62, 0xbfb8aa3b, v61
	v_exp_f32_e32 v62, v62
	s_nop 0
	v_add_f32_e32 v62, 1.0, v62
	v_rcp_f32_e32 v149, v62
	s_nop 0
	v_pk_mul_f32 v[60:61], v[148:149], v[60:61]
	s_nop 0
	v_add_f32_e32 v60, v63, v60
	v_mul_f32_e32 v60, v60, v61
	v_bfe_u32 v61, v60, 16, 1
	v_add3_u32 v61, v60, v61, s85
	v_fmac_f32_e32 v90, v60, v60
	global_store_short_d16_hi v[64:65], v61, off offset:96

.LBB0_1768:
	v_lshlrev_b64 v[234:235], 12, v[88:89]
	v_lshl_add_u64 v[234:235], v[152:153], 0, v[234:235]
	v_fmac_f32_e32 v83, v91, v94
	v_and_b32_e32 v90, 0xffff0000, v155
	v_lshlrev_b32_e32 v91, 16, v242
	v_mul_f32_e32 v82, 0xbfb8aa3b, v91
	v_exp_f32_e32 v82, v82
	s_nop 0
	v_add_f32_e32 v82, 1.0, v82
	v_rcp_f32_e32 v149, v82
	s_nop 0
	v_pk_mul_f32 v[90:91], v[148:149], v[90:91]
	s_nop 0
	v_add_f32_e32 v82, v83, v90
	v_mul_f32_e32 v82, v82, v91
	v_bfe_u32 v83, v82, 16, 1
	v_add3_u32 v83, v82, v83, s85
	v_mul_f32_e32 v90, v82, v82
	global_store_short_d16_hi v[234:235], v83, off
	s_or_b64 exec, exec, s[76:77]
	ds_read_b64 v[82:83], v225 offset:38144
	s_and_saveexec_b64 s[76:77], vcc
	s_cbranch_execz .LBB0_1748
.LBB0_1769:
	v_lshlrev_b64 v[234:235], 12, v[2:3]
	v_lshl_add_u64 v[234:235], v[152:153], 0, v[234:235]
	s_waitcnt lgkmcnt(0)
	v_lshlrev_b32_e32 v236, 16, v82
	v_fma_f32 v72, v84, v231, v72
	v_lshlrev_b32_e32 v237, 16, v243
	v_mul_f32_e32 v91, 0xbfb8aa3b, v237
	v_exp_f32_e32 v91, v91
	s_nop 0
	v_add_f32_e32 v91, 1.0, v91
	v_rcp_f32_e32 v149, v91
	s_nop 0
	v_pk_mul_f32 v[236:237], v[148:149], v[236:237]
	s_nop 0
	v_add_f32_e32 v72, v72, v236
	v_mul_f32_e32 v72, v72, v237
	v_bfe_u32 v84, v72, 16, 1
	v_add3_u32 v84, v72, v84, s85
	v_fmac_f32_e32 v229, v72, v72
	global_store_short_d16_hi v[234:235], v84, off offset:32
	s_or_b64 exec, exec, s[76:77]
	s_and_saveexec_b64 s[76:77], s[54:55]
	s_cbranch_execz .LBB0_1749
.LBB0_1770:
	v_lshlrev_b64 v[234:235], 12, v[92:93]
	v_lshl_add_u64 v[234:235], v[152:153], 0, v[234:235]
	s_waitcnt lgkmcnt(0)
	v_and_b32_e32 v236, 0xffff0000, v82
	v_fma_f32 v82, v85, v232, v73
	v_lshlrev_b32_e32 v237, 16, v244
	v_mul_f32_e32 v72, 0xbfb8aa3b, v237
	v_exp_f32_e32 v72, v72
	s_nop 0
	v_add_f32_e32 v72, 1.0, v72
	v_rcp_f32_e32 v149, v72
	s_nop 0
	v_pk_mul_f32 v[72:73], v[148:149], v[236:237]
	s_nop 0
	v_add_f32_e32 v72, v82, v72
	v_mul_f32_e32 v72, v72, v73
	v_bfe_u32 v73, v72, 16, 1
	v_add3_u32 v73, v72, v73, s85
	v_fmac_f32_e32 v230, v72, v72
	global_store_short_d16_hi v[234:235], v73, off offset:32
	s_or_b64 exec, exec, s[76:77]
	s_and_saveexec_b64 s[76:77], s[56:57]
	s_cbranch_execz .LBB0_1750
.LBB0_1771:
	v_lshlrev_b64 v[72:73], 12, v[80:81]
	v_lshl_add_u64 v[72:73], v[152:153], 0, v[72:73]
	s_waitcnt lgkmcnt(0)
	v_lshlrev_b32_e32 v84, 16, v83
	v_fma_f32 v74, v86, v154, v74
	v_lshlrev_b32_e32 v85, 16, v245
	v_mul_f32_e32 v82, 0xbfb8aa3b, v85
	v_exp_f32_e32 v82, v82
	s_nop 0
	v_add_f32_e32 v82, 1.0, v82
	v_rcp_f32_e32 v149, v82
	s_nop 0
	v_pk_mul_f32 v[84:85], v[148:149], v[84:85]
	s_nop 0
	v_add_f32_e32 v74, v74, v84
	v_mul_f32_e32 v74, v74, v85
	v_bfe_u32 v82, v74, 16, 1
	v_add3_u32 v82, v74, v82, s85
	v_fmac_f32_e32 v228, v74, v74
	global_store_short_d16_hi v[72:73], v82, off offset:32
	s_or_b64 exec, exec, s[76:77]
	s_and_saveexec_b64 s[76:77], s[58:59]
	s_cbranch_execz .LBB0_1751
.LBB0_1772:
	s_waitcnt lgkmcnt(0)
	v_and_b32_e32 v72, 0xffff0000, v83
	v_lshlrev_b64 v[82:83], 12, v[88:89]
	v_lshl_add_u64 v[82:83], v[152:153], 0, v[82:83]
	v_fmac_f32_e32 v75, v87, v94
	v_lshlrev_b32_e32 v73, 16, v246
	v_mul_f32_e32 v74, 0xbfb8aa3b, v73
	v_exp_f32_e32 v74, v74
	s_nop 0
	v_add_f32_e32 v74, 1.0, v74
	v_rcp_f32_e32 v149, v74
	s_nop 0
	v_pk_mul_f32 v[72:73], v[148:149], v[72:73]
	s_nop 0
	v_add_f32_e32 v72, v75, v72
	v_mul_f32_e32 v72, v72, v73
	v_bfe_u32 v73, v72, 16, 1
	v_add3_u32 v73, v72, v73, s85
	v_fmac_f32_e32 v90, v72, v72
	global_store_short_d16_hi v[82:83], v73, off offset:32
	s_or_b64 exec, exec, s[76:77]
	ds_read_b64 v[72:73], v225 offset:40448
	s_and_saveexec_b64 s[76:77], vcc
	s_cbranch_execz .LBB0_1752
.LBB0_1773:
	v_lshlrev_b64 v[74:75], 12, v[2:3]
	v_lshl_add_u64 v[74:75], v[152:153], 0, v[74:75]
	s_waitcnt lgkmcnt(1)
	v_fma_f32 v68, v76, v231, v68
	v_lshlrev_b32_e32 v83, 16, v247
	v_mul_f32_e32 v82, 0xbfb8aa3b, v83
	v_exp_f32_e32 v82, v82
	s_nop 0
	v_add_f32_e32 v82, 1.0, v82
	v_rcp_f32_e32 v149, v82
	s_waitcnt lgkmcnt(0)
	v_lshlrev_b32_e32 v82, 16, v72
	v_pk_mul_f32 v[82:83], v[148:149], v[82:83]
	s_nop 0
	v_add_f32_e32 v68, v68, v82
	v_mul_f32_e32 v68, v68, v83
	v_bfe_u32 v76, v68, 16, 1
	v_add3_u32 v76, v68, v76, s85
	v_fmac_f32_e32 v229, v68, v68
	global_store_short_d16_hi v[74:75], v76, off offset:64
	s_or_b64 exec, exec, s[76:77]
	s_and_saveexec_b64 s[76:77], s[54:55]
	s_cbranch_execz .LBB0_1753
.LBB0_1774:
	v_lshlrev_b64 v[74:75], 12, v[92:93]
	v_lshl_add_u64 v[74:75], v[152:153], 0, v[74:75]
	s_waitcnt lgkmcnt(0)
	v_and_b32_e32 v82, 0xffff0000, v72
	v_fma_f32 v72, v77, v232, v69
	v_lshlrev_b32_e32 v83, 16, v248
	v_mul_f32_e32 v68, 0xbfb8aa3b, v83
	v_exp_f32_e32 v68, v68
	s_nop 0
	v_add_f32_e32 v68, 1.0, v68
	v_rcp_f32_e32 v149, v68
	s_nop 0
	v_pk_mul_f32 v[68:69], v[148:149], v[82:83]
	s_nop 0
	v_add_f32_e32 v68, v72, v68
	v_mul_f32_e32 v68, v68, v69
	v_bfe_u32 v69, v68, 16, 1
	v_add3_u32 v69, v68, v69, s85
	v_fmac_f32_e32 v230, v68, v68
	global_store_short_d16_hi v[74:75], v69, off offset:64
	s_or_b64 exec, exec, s[76:77]
	s_and_saveexec_b64 s[76:77], s[56:57]
	s_cbranch_execz .LBB0_1754
.LBB0_1775:
	v_lshlrev_b64 v[68:69], 12, v[80:81]
	v_lshl_add_u64 v[68:69], v[152:153], 0, v[68:69]
	s_waitcnt lgkmcnt(0)
	v_lshlrev_b32_e32 v74, 16, v73
	v_fma_f32 v70, v78, v154, v70
	v_lshlrev_b32_e32 v75, 16, v249
	v_mul_f32_e32 v72, 0xbfb8aa3b, v75
	v_exp_f32_e32 v72, v72
	s_nop 0
	v_add_f32_e32 v72, 1.0, v72
	v_rcp_f32_e32 v149, v72
	s_nop 0
	v_pk_mul_f32 v[74:75], v[148:149], v[74:75]
	s_nop 0
	v_add_f32_e32 v70, v70, v74
	v_mul_f32_e32 v70, v70, v75
	v_bfe_u32 v72, v70, 16, 1
	v_add3_u32 v72, v70, v72, s85
	v_fmac_f32_e32 v228, v70, v70
	global_store_short_d16_hi v[68:69], v72, off offset:64
	s_or_b64 exec, exec, s[76:77]
	s_and_saveexec_b64 s[76:77], s[58:59]
	s_cbranch_execz .LBB0_1755
.LBB0_1776:
	s_waitcnt lgkmcnt(0)
	v_and_b32_e32 v68, 0xffff0000, v73
	v_lshlrev_b64 v[72:73], 12, v[88:89]
	v_lshl_add_u64 v[72:73], v[152:153], 0, v[72:73]
	v_fmac_f32_e32 v71, v79, v94
	v_lshlrev_b32_e32 v69, 16, v250
	v_mul_f32_e32 v70, 0xbfb8aa3b, v69
	v_exp_f32_e32 v70, v70
	s_nop 0
	v_add_f32_e32 v70, 1.0, v70
	v_rcp_f32_e32 v149, v70
	s_nop 0
	v_pk_mul_f32 v[68:69], v[148:149], v[68:69]
	s_nop 0
	v_add_f32_e32 v68, v71, v68
	v_mul_f32_e32 v68, v68, v69
	v_bfe_u32 v69, v68, 16, 1
	v_add3_u32 v69, v68, v69, s85
	v_fmac_f32_e32 v90, v68, v68
	global_store_short_d16_hi v[72:73], v69, off offset:64
	s_or_b64 exec, exec, s[76:77]
	ds_read_b64 v[68:69], v225 offset:42752
	s_and_saveexec_b64 s[76:77], vcc
	s_cbranch_execz .LBB0_1756
.LBB0_1777:
	v_lshlrev_b64 v[70:71], 12, v[2:3]
	v_lshl_add_u64 v[70:71], v[152:153], 0, v[70:71]
	s_waitcnt lgkmcnt(1)
	v_fma_f32 v60, v64, v231, v60
	v_lshlrev_b32_e32 v73, 16, v251
	v_mul_f32_e32 v72, 0xbfb8aa3b, v73
	v_exp_f32_e32 v72, v72
	s_nop 0
	v_add_f32_e32 v72, 1.0, v72
	v_rcp_f32_e32 v149, v72
	s_waitcnt lgkmcnt(0)
	v_lshlrev_b32_e32 v72, 16, v68
	v_pk_mul_f32 v[72:73], v[148:149], v[72:73]
	s_nop 0
	v_add_f32_e32 v60, v60, v72
	v_mul_f32_e32 v60, v60, v73
	v_bfe_u32 v64, v60, 16, 1
	v_add3_u32 v64, v60, v64, s85
	v_fmac_f32_e32 v229, v60, v60
	global_store_short_d16_hi v[70:71], v64, off offset:96
	s_or_b64 exec, exec, s[76:77]
	s_and_saveexec_b64 s[76:77], s[54:55]
	s_cbranch_execz .LBB0_1757
.LBB0_1778:
	s_waitcnt lgkmcnt(0)
	v_and_b32_e32 v60, 0xffff0000, v68
	v_fma_f32 v68, v65, v232, v61
	v_lshlrev_b64 v[64:65], 12, v[92:93]
	v_lshl_add_u64 v[64:65], v[152:153], 0, v[64:65]
	v_lshlrev_b32_e32 v61, 16, v252
	v_mul_f32_e32 v70, 0xbfb8aa3b, v61
	v_exp_f32_e32 v70, v70
	s_nop 0
	v_add_f32_e32 v70, 1.0, v70
	v_rcp_f32_e32 v149, v70
	s_nop 0
	v_pk_mul_f32 v[60:61], v[148:149], v[60:61]
	s_nop 0
	v_add_f32_e32 v60, v68, v60
	v_mul_f32_e32 v60, v60, v61
	v_bfe_u32 v61, v60, 16, 1
	v_add3_u32 v61, v60, v61, s85
	v_fmac_f32_e32 v230, v60, v60
	global_store_short_d16_hi v[64:65], v61, off offset:96
	s_or_b64 exec, exec, s[76:77]
	s_and_saveexec_b64 s[76:77], s[56:57]
	s_cbranch_execz .LBB0_1758
.LBB0_1779:
	v_lshlrev_b64 v[64:65], 12, v[80:81]
	v_lshl_add_u64 v[64:65], v[152:153], 0, v[64:65]
	v_fma_f32 v62, v66, v154, v62
	s_waitcnt lgkmcnt(0)
	v_lshlrev_b32_e32 v60, 16, v69
	v_lshlrev_b32_e32 v61, 16, v253
	v_mul_f32_e32 v66, 0xbfb8aa3b, v61
	v_exp_f32_e32 v66, v66
	s_nop 0
	v_add_f32_e32 v66, 1.0, v66
	v_rcp_f32_e32 v149, v66
	s_nop 0
	v_pk_mul_f32 v[60:61], v[148:149], v[60:61]
	s_nop 0
	v_add_f32_e32 v60, v62, v60
	v_mul_f32_e32 v60, v60, v61
	v_bfe_u32 v61, v60, 16, 1
	v_add3_u32 v61, v60, v61, s85
	v_fmac_f32_e32 v228, v60, v60
	global_store_short_d16_hi v[64:65], v61, off offset:96
	s_or_b64 exec, exec, s[76:77]
	s_and_saveexec_b64 s[76:77], s[58:59]
	s_cbranch_execnz .LBB0_1759
	s_branch .LBB0_1760
